# attention: MFMA-result wait pads reduced to the required 12 wait states, inline-asm pads between v_max3 removed (on top of residual epilogue rewrite)
# speedup vs baseline: 1.0151x; 1.0132x over previous
.LBB0_837:
	s_nop 3
	s_xor_b64 s[12:13], s[54:55], -1
	v_max3_f32 v0, v64, v65, v80
	v_max3_f32 v1, v66, v67, v81
	v_max3_f32 v0, v0, v82, v83
	v_max3_f32 v1, v1, v70, v71
	v_max3_f32 v0, v0, v68, v69
	v_max3_f32 v1, v1, v86, v87
	v_max3_f32 v0, v0, v84, v85
	v_max3_f32 v1, v1, v74, v75
	v_max3_f32 v0, v0, v72, v73
	v_max3_f32 v1, v1, v90, v91
	v_max3_f32 v0, v0, v88, v89
	v_max3_f32 v1, v1, v78, v79
	v_max3_f32 v0, v0, v76, v77
	v_max3_f32 v1, v1, v94, v95
	v_max3_f32 v0, v0, v92, v93
	v_max_f32_e32 v1, v1, v1
	v_max_f32_e32 v0, v0, v0
	v_max_f32_e32 v0, v0, v1
	v_mov_b32_e32 v1, v0
	s_nop 1
	v_permlane32_swap_b32_e32 v0, v1
	v_max_f32_e32 v1, v1, v1
	v_max_f32_e32 v0, v0, v0
	v_max_f32_e32 v1, v0, v1
	v_cmp_lt_f32_e32 vcc, s14, v1
	s_or_b64 s[16:17], vcc, s[12:13]
	v_cndmask_b32_e64 v0, 0, 1, s[16:17]
	v_cmp_ne_u32_e32 vcc, 0, v0
	s_cbranch_vccz .LBB0_843
	s_and_saveexec_b64 s[16:17], s[12:13]
	s_xor_b64 s[12:13], exec, s[16:17]
	v_cmp_lg_f32_e64 s[54:55], s5, v1
	s_nop 1
	v_cndmask_b32_e64 v48, 0, v1, s[54:55]
	s_or_saveexec_b64 s[12:13], s[12:13]
	v_mov_b32_e32 v0, 1.0
	s_xor_b64 exec, exec, s[12:13]
	v_max_f32_e32 v0, v1, v1
	v_max_f32_e32 v48, 0, v0
	v_exp_f32_e64 v0, -v48
	s_or_b64 s[54:55], s[54:55], exec
	s_or_b64 exec, exec, s[12:13]
	v_add_f32_e32 v181, v181, v48
	v_pk_add_f32 v[64:65], v[64:65], v[48:49] op_sel_hi:[1,0] neg_lo:[0,1] neg_hi:[0,1]
	v_pk_add_f32 v[80:81], v[80:81], v[48:49] op_sel_hi:[1,0] neg_lo:[0,1] neg_hi:[0,1]
	v_pk_add_f32 v[66:67], v[66:67], v[48:49] op_sel_hi:[1,0] neg_lo:[0,1] neg_hi:[0,1]
	v_pk_add_f32 v[82:83], v[82:83], v[48:49] op_sel_hi:[1,0] neg_lo:[0,1] neg_hi:[0,1]
	v_pk_add_f32 v[68:69], v[68:69], v[48:49] op_sel_hi:[1,0] neg_lo:[0,1] neg_hi:[0,1]
	v_pk_add_f32 v[84:85], v[84:85], v[48:49] op_sel_hi:[1,0] neg_lo:[0,1] neg_hi:[0,1]
	v_pk_add_f32 v[70:71], v[70:71], v[48:49] op_sel_hi:[1,0] neg_lo:[0,1] neg_hi:[0,1]
	v_pk_add_f32 v[86:87], v[86:87], v[48:49] op_sel_hi:[1,0] neg_lo:[0,1] neg_hi:[0,1]
	v_pk_add_f32 v[72:73], v[72:73], v[48:49] op_sel_hi:[1,0] neg_lo:[0,1] neg_hi:[0,1]
	v_pk_add_f32 v[88:89], v[88:89], v[48:49] op_sel_hi:[1,0] neg_lo:[0,1] neg_hi:[0,1]
	v_pk_add_f32 v[74:75], v[74:75], v[48:49] op_sel_hi:[1,0] neg_lo:[0,1] neg_hi:[0,1]
	v_pk_add_f32 v[90:91], v[90:91], v[48:49] op_sel_hi:[1,0] neg_lo:[0,1] neg_hi:[0,1]
	v_pk_add_f32 v[76:77], v[76:77], v[48:49] op_sel_hi:[1,0] neg_lo:[0,1] neg_hi:[0,1]
	v_pk_add_f32 v[92:93], v[92:93], v[48:49] op_sel_hi:[1,0] neg_lo:[0,1] neg_hi:[0,1]
	v_pk_add_f32 v[78:79], v[78:79], v[48:49] op_sel_hi:[1,0] neg_lo:[0,1] neg_hi:[0,1]
	v_pk_add_f32 v[94:95], v[94:95], v[48:49] op_sel_hi:[1,0] neg_lo:[0,1] neg_hi:[0,1]
	v_xor_b32_e32 v48, 0x80000000, v181
	v_mul_f32_e32 v180, v180, v0
	v_pk_mul_f32 v[46:47], v[46:47], v[0:1] op_sel_hi:[1,0]
	v_pk_mul_f32 v[44:45], v[44:45], v[0:1] op_sel_hi:[1,0]
	v_pk_mul_f32 v[42:43], v[42:43], v[0:1] op_sel_hi:[1,0]
	v_pk_mul_f32 v[40:41], v[40:41], v[0:1] op_sel_hi:[1,0]
	v_pk_mul_f32 v[38:39], v[38:39], v[0:1] op_sel_hi:[1,0]
	v_pk_mul_f32 v[36:37], v[36:37], v[0:1] op_sel_hi:[1,0]
	v_pk_mul_f32 v[34:35], v[34:35], v[0:1] op_sel_hi:[1,0]
	v_pk_mul_f32 v[32:33], v[32:33], v[0:1] op_sel_hi:[1,0]
	v_pk_mul_f32 v[30:31], v[30:31], v[0:1] op_sel_hi:[1,0]
	v_pk_mul_f32 v[28:29], v[28:29], v[0:1] op_sel_hi:[1,0]
	v_pk_mul_f32 v[26:27], v[26:27], v[0:1] op_sel_hi:[1,0]
	v_pk_mul_f32 v[24:25], v[24:25], v[0:1] op_sel_hi:[1,0]
	v_pk_mul_f32 v[22:23], v[22:23], v[0:1] op_sel_hi:[1,0]
	v_pk_mul_f32 v[20:21], v[20:21], v[0:1] op_sel_hi:[1,0]
	v_pk_mul_f32 v[18:19], v[18:19], v[0:1] op_sel_hi:[1,0]
	v_pk_mul_f32 v[16:17], v[16:17], v[0:1] op_sel_hi:[1,0]
	v_mov_b32_e32 v49, v48
	v_mov_b32_e32 v50, v48
	v_mov_b32_e32 v51, v48
	v_mov_b32_e32 v52, v48
	v_mov_b32_e32 v53, v48
	v_mov_b32_e32 v54, v48
	v_mov_b32_e32 v55, v48
	v_mov_b32_e32 v56, v48
	v_mov_b32_e32 v57, v48
	v_mov_b32_e32 v58, v48
	v_mov_b32_e32 v59, v48
	v_mov_b32_e32 v60, v48
	v_mov_b32_e32 v61, v48
	v_mov_b32_e32 v62, v48
	v_mov_b32_e32 v63, v48

.LBB0_850:
	s_nop 9
	s_nop 0
	v_max3_f32 v0, v64, v65, v80
	v_max3_f32 v1, v66, v67, v81
	v_max3_f32 v0, v0, v82, v83
	v_max3_f32 v1, v1, v70, v71
	v_max3_f32 v0, v0, v68, v69
	v_max3_f32 v1, v1, v86, v87
	v_max3_f32 v0, v0, v84, v85
	v_max3_f32 v1, v1, v74, v75
	v_max3_f32 v0, v0, v72, v73
	v_max3_f32 v1, v1, v90, v91
	v_max3_f32 v0, v0, v88, v89
	v_max3_f32 v1, v1, v78, v79
	v_max3_f32 v0, v0, v76, v77
	v_max3_f32 v1, v1, v94, v95
	v_max3_f32 v0, v0, v92, v93
	v_max_f32_e32 v1, v1, v1
	v_max_f32_e32 v0, v0, v0
	v_max_f32_e32 v0, v0, v1
	v_mov_b32_e32 v1, v0
	s_nop 1
	v_permlane32_swap_b32_e32 v0, v1
	v_max_f32_e32 v1, v1, v1
	v_max_f32_e32 v0, v0, v0
	v_max_f32_e32 v1, v0, v1
	v_cmp_lt_f32_e32 vcc, s14, v1
	s_or_b64 s[16:17], vcc, s[12:13]
	v_cndmask_b32_e64 v0, 0, 1, s[16:17]
	v_cmp_ne_u32_e32 vcc, 0, v0
	s_cbranch_vccz .LBB0_856
	s_and_saveexec_b64 s[16:17], s[12:13]
	s_xor_b64 s[12:13], exec, s[16:17]
	v_cmp_lg_f32_e64 s[54:55], s5, v1
	s_nop 1
	v_cndmask_b32_e64 v48, 0, v1, s[54:55]
	s_or_saveexec_b64 s[12:13], s[12:13]
	v_mov_b32_e32 v0, 1.0
	s_xor_b64 exec, exec, s[12:13]
	v_max_f32_e32 v0, v1, v1
	v_max_f32_e32 v48, 0, v0
	v_exp_f32_e64 v0, -v48
	s_or_b64 s[54:55], s[54:55], exec
	s_or_b64 exec, exec, s[12:13]
	v_add_f32_e32 v181, v181, v48
	v_pk_add_f32 v[64:65], v[64:65], v[48:49] op_sel_hi:[1,0] neg_lo:[0,1] neg_hi:[0,1]
	v_pk_add_f32 v[80:81], v[80:81], v[48:49] op_sel_hi:[1,0] neg_lo:[0,1] neg_hi:[0,1]
	v_pk_add_f32 v[66:67], v[66:67], v[48:49] op_sel_hi:[1,0] neg_lo:[0,1] neg_hi:[0,1]
	v_pk_add_f32 v[82:83], v[82:83], v[48:49] op_sel_hi:[1,0] neg_lo:[0,1] neg_hi:[0,1]
	v_pk_add_f32 v[68:69], v[68:69], v[48:49] op_sel_hi:[1,0] neg_lo:[0,1] neg_hi:[0,1]
	v_pk_add_f32 v[84:85], v[84:85], v[48:49] op_sel_hi:[1,0] neg_lo:[0,1] neg_hi:[0,1]
	v_pk_add_f32 v[70:71], v[70:71], v[48:49] op_sel_hi:[1,0] neg_lo:[0,1] neg_hi:[0,1]
	v_pk_add_f32 v[86:87], v[86:87], v[48:49] op_sel_hi:[1,0] neg_lo:[0,1] neg_hi:[0,1]
	v_pk_add_f32 v[72:73], v[72:73], v[48:49] op_sel_hi:[1,0] neg_lo:[0,1] neg_hi:[0,1]
	v_pk_add_f32 v[88:89], v[88:89], v[48:49] op_sel_hi:[1,0] neg_lo:[0,1] neg_hi:[0,1]
	v_pk_add_f32 v[74:75], v[74:75], v[48:49] op_sel_hi:[1,0] neg_lo:[0,1] neg_hi:[0,1]
	v_pk_add_f32 v[90:91], v[90:91], v[48:49] op_sel_hi:[1,0] neg_lo:[0,1] neg_hi:[0,1]
	v_pk_add_f32 v[76:77], v[76:77], v[48:49] op_sel_hi:[1,0] neg_lo:[0,1] neg_hi:[0,1]
	v_pk_add_f32 v[92:93], v[92:93], v[48:49] op_sel_hi:[1,0] neg_lo:[0,1] neg_hi:[0,1]
	v_pk_add_f32 v[78:79], v[78:79], v[48:49] op_sel_hi:[1,0] neg_lo:[0,1] neg_hi:[0,1]
	v_pk_add_f32 v[94:95], v[94:95], v[48:49] op_sel_hi:[1,0] neg_lo:[0,1] neg_hi:[0,1]
	v_xor_b32_e32 v48, 0x80000000, v181
	v_mul_f32_e32 v180, v180, v0
	v_pk_mul_f32 v[46:47], v[46:47], v[0:1] op_sel_hi:[1,0]
	v_pk_mul_f32 v[44:45], v[44:45], v[0:1] op_sel_hi:[1,0]
	v_pk_mul_f32 v[42:43], v[42:43], v[0:1] op_sel_hi:[1,0]
	v_pk_mul_f32 v[40:41], v[40:41], v[0:1] op_sel_hi:[1,0]
	v_pk_mul_f32 v[38:39], v[38:39], v[0:1] op_sel_hi:[1,0]
	v_pk_mul_f32 v[36:37], v[36:37], v[0:1] op_sel_hi:[1,0]
	v_pk_mul_f32 v[34:35], v[34:35], v[0:1] op_sel_hi:[1,0]
	v_pk_mul_f32 v[32:33], v[32:33], v[0:1] op_sel_hi:[1,0]
	v_pk_mul_f32 v[30:31], v[30:31], v[0:1] op_sel_hi:[1,0]
	v_pk_mul_f32 v[28:29], v[28:29], v[0:1] op_sel_hi:[1,0]
	v_pk_mul_f32 v[26:27], v[26:27], v[0:1] op_sel_hi:[1,0]
	v_pk_mul_f32 v[24:25], v[24:25], v[0:1] op_sel_hi:[1,0]
	v_pk_mul_f32 v[22:23], v[22:23], v[0:1] op_sel_hi:[1,0]
	v_pk_mul_f32 v[20:21], v[20:21], v[0:1] op_sel_hi:[1,0]
	v_pk_mul_f32 v[18:19], v[18:19], v[0:1] op_sel_hi:[1,0]
	v_pk_mul_f32 v[16:17], v[16:17], v[0:1] op_sel_hi:[1,0]
	v_mov_b32_e32 v49, v48
	v_mov_b32_e32 v50, v48
	v_mov_b32_e32 v51, v48
	v_mov_b32_e32 v52, v48
	v_mov_b32_e32 v53, v48
	v_mov_b32_e32 v54, v48
	v_mov_b32_e32 v55, v48
	v_mov_b32_e32 v56, v48
	v_mov_b32_e32 v57, v48
	v_mov_b32_e32 v58, v48
	v_mov_b32_e32 v59, v48
	v_mov_b32_e32 v60, v48
	v_mov_b32_e32 v61, v48
	v_mov_b32_e32 v62, v48
	v_mov_b32_e32 v63, v48

.LBB0_878:
	s_nop 8
	s_xor_b64 s[16:17], s[52:53], -1
	v_max3_f32 v0, v80, v81, v96
	v_max3_f32 v1, v82, v83, v97
	v_max3_f32 v0, v0, v98, v99
	v_max3_f32 v1, v1, v86, v87
	v_max3_f32 v0, v0, v84, v85
	v_max3_f32 v1, v1, v102, v103
	v_max3_f32 v0, v0, v100, v101
	v_max3_f32 v1, v1, v90, v91
	v_max3_f32 v0, v0, v88, v89
	v_max3_f32 v1, v1, v106, v107
	v_max3_f32 v0, v0, v104, v105
	v_max3_f32 v1, v1, v94, v95
	v_max3_f32 v0, v0, v92, v93
	v_max3_f32 v1, v1, v110, v111
	v_max3_f32 v0, v0, v108, v109
	v_max_f32_e32 v1, v1, v1
	v_max_f32_e32 v0, v0, v0
	v_max_f32_e32 v0, v0, v1
	v_mov_b32_e32 v1, v0
	s_nop 1
	v_permlane32_swap_b32_e32 v0, v1
	v_max_f32_e32 v1, v1, v1
	v_max_f32_e32 v0, v0, v0
	v_max_f32_e32 v1, v0, v1
	v_cmp_lt_f32_e32 vcc, s14, v1
	s_or_b64 s[18:19], vcc, s[16:17]
	v_cndmask_b32_e64 v0, 0, 1, s[18:19]
	v_cmp_ne_u32_e32 vcc, 0, v0
	s_cbranch_vccz .LBB0_884
	s_and_saveexec_b64 s[18:19], s[16:17]
	s_xor_b64 s[16:17], exec, s[18:19]
	v_cmp_lg_f32_e64 s[52:53], s5, v1
	s_nop 1
	v_cndmask_b32_e64 v48, 0, v1, s[52:53]
	s_or_saveexec_b64 s[16:17], s[16:17]
	v_mov_b32_e32 v0, 1.0
	s_xor_b64 exec, exec, s[16:17]
	v_max_f32_e32 v0, v1, v1
	v_max_f32_e32 v48, 0, v0
	v_exp_f32_e64 v0, -v48
	s_or_b64 s[52:53], s[52:53], exec
	s_or_b64 exec, exec, s[16:17]
	v_add_f32_e32 v219, v219, v48
	v_pk_add_f32 v[80:81], v[80:81], v[48:49] op_sel_hi:[1,0] neg_lo:[0,1] neg_hi:[0,1]
	v_pk_add_f32 v[96:97], v[96:97], v[48:49] op_sel_hi:[1,0] neg_lo:[0,1] neg_hi:[0,1]
	v_pk_add_f32 v[82:83], v[82:83], v[48:49] op_sel_hi:[1,0] neg_lo:[0,1] neg_hi:[0,1]
	v_pk_add_f32 v[98:99], v[98:99], v[48:49] op_sel_hi:[1,0] neg_lo:[0,1] neg_hi:[0,1]
	v_pk_add_f32 v[84:85], v[84:85], v[48:49] op_sel_hi:[1,0] neg_lo:[0,1] neg_hi:[0,1]
	v_pk_add_f32 v[100:101], v[100:101], v[48:49] op_sel_hi:[1,0] neg_lo:[0,1] neg_hi:[0,1]
	v_pk_add_f32 v[86:87], v[86:87], v[48:49] op_sel_hi:[1,0] neg_lo:[0,1] neg_hi:[0,1]
	v_pk_add_f32 v[102:103], v[102:103], v[48:49] op_sel_hi:[1,0] neg_lo:[0,1] neg_hi:[0,1]
	v_pk_add_f32 v[88:89], v[88:89], v[48:49] op_sel_hi:[1,0] neg_lo:[0,1] neg_hi:[0,1]
	v_pk_add_f32 v[104:105], v[104:105], v[48:49] op_sel_hi:[1,0] neg_lo:[0,1] neg_hi:[0,1]
	v_pk_add_f32 v[90:91], v[90:91], v[48:49] op_sel_hi:[1,0] neg_lo:[0,1] neg_hi:[0,1]
	v_pk_add_f32 v[106:107], v[106:107], v[48:49] op_sel_hi:[1,0] neg_lo:[0,1] neg_hi:[0,1]
	v_pk_add_f32 v[92:93], v[92:93], v[48:49] op_sel_hi:[1,0] neg_lo:[0,1] neg_hi:[0,1]
	v_pk_add_f32 v[108:109], v[108:109], v[48:49] op_sel_hi:[1,0] neg_lo:[0,1] neg_hi:[0,1]
	v_pk_add_f32 v[94:95], v[94:95], v[48:49] op_sel_hi:[1,0] neg_lo:[0,1] neg_hi:[0,1]
	v_pk_add_f32 v[110:111], v[110:111], v[48:49] op_sel_hi:[1,0] neg_lo:[0,1] neg_hi:[0,1]
	v_xor_b32_e32 v48, 0x80000000, v219
	v_mul_f32_e32 v209, v209, v0
	v_pk_mul_f32 v[46:47], v[46:47], v[0:1] op_sel_hi:[1,0]
	v_pk_mul_f32 v[44:45], v[44:45], v[0:1] op_sel_hi:[1,0]
	v_pk_mul_f32 v[42:43], v[42:43], v[0:1] op_sel_hi:[1,0]
	v_pk_mul_f32 v[40:41], v[40:41], v[0:1] op_sel_hi:[1,0]
	v_pk_mul_f32 v[38:39], v[38:39], v[0:1] op_sel_hi:[1,0]
	v_pk_mul_f32 v[36:37], v[36:37], v[0:1] op_sel_hi:[1,0]
	v_pk_mul_f32 v[34:35], v[34:35], v[0:1] op_sel_hi:[1,0]
	v_pk_mul_f32 v[32:33], v[32:33], v[0:1] op_sel_hi:[1,0]
	v_pk_mul_f32 v[30:31], v[30:31], v[0:1] op_sel_hi:[1,0]
	v_pk_mul_f32 v[28:29], v[28:29], v[0:1] op_sel_hi:[1,0]
	v_pk_mul_f32 v[26:27], v[26:27], v[0:1] op_sel_hi:[1,0]
	v_pk_mul_f32 v[24:25], v[24:25], v[0:1] op_sel_hi:[1,0]
	v_pk_mul_f32 v[22:23], v[22:23], v[0:1] op_sel_hi:[1,0]
	v_pk_mul_f32 v[20:21], v[20:21], v[0:1] op_sel_hi:[1,0]
	v_pk_mul_f32 v[18:19], v[18:19], v[0:1] op_sel_hi:[1,0]
	v_pk_mul_f32 v[16:17], v[16:17], v[0:1] op_sel_hi:[1,0]
	v_mov_b32_e32 v49, v48
	v_mov_b32_e32 v50, v48
	v_mov_b32_e32 v51, v48
	v_mov_b32_e32 v52, v48
	v_mov_b32_e32 v53, v48
	v_mov_b32_e32 v54, v48
	v_mov_b32_e32 v55, v48
	v_mov_b32_e32 v56, v48
	v_mov_b32_e32 v57, v48
	v_mov_b32_e32 v58, v48
	v_mov_b32_e32 v59, v48
	v_mov_b32_e32 v60, v48
	v_mov_b32_e32 v61, v48
	v_mov_b32_e32 v62, v48
	v_mov_b32_e32 v63, v48
	v_mov_b32_e32 v79, v48
	v_mov_b32_e32 v78, v48
	v_mov_b32_e32 v77, v48
	v_mov_b32_e32 v76, v48
	v_mov_b32_e32 v75, v48
	v_mov_b32_e32 v74, v48
	v_mov_b32_e32 v73, v48
	v_mov_b32_e32 v72, v48
	v_mov_b32_e32 v71, v48
	v_mov_b32_e32 v70, v48
	v_mov_b32_e32 v69, v48
	v_mov_b32_e32 v68, v48
	v_mov_b32_e32 v67, v48
	v_mov_b32_e32 v66, v48
	v_mov_b32_e32 v65, v48
	v_mov_b32_e32 v64, v48
	s_branch .LBB0_885

.LBB0_892:
	s_nop 8
	s_xor_b64 s[12:13], s[52:53], -1
	v_max3_f32 v0, v80, v81, v96
	v_max3_f32 v1, v82, v83, v97
	v_max3_f32 v0, v0, v98, v99
	v_max3_f32 v1, v1, v86, v87
	v_max3_f32 v0, v0, v84, v85
	v_max3_f32 v1, v1, v102, v103
	v_max3_f32 v0, v0, v100, v101
	v_max3_f32 v1, v1, v90, v91
	v_max3_f32 v0, v0, v88, v89
	v_max3_f32 v1, v1, v106, v107
	v_max3_f32 v0, v0, v104, v105
	v_max3_f32 v1, v1, v94, v95
	v_max3_f32 v0, v0, v92, v93
	v_max3_f32 v1, v1, v110, v111
	v_max3_f32 v0, v0, v108, v109
	v_max_f32_e32 v1, v1, v1
	v_max_f32_e32 v0, v0, v0
	v_max_f32_e32 v0, v0, v1
	v_mov_b32_e32 v1, v0
	s_nop 1
	v_permlane32_swap_b32_e32 v0, v1
	v_max_f32_e32 v1, v1, v1
	v_max_f32_e32 v0, v0, v0
	v_max_f32_e32 v1, v0, v1
	v_cmp_lt_f32_e32 vcc, s14, v1
	s_or_b64 s[16:17], vcc, s[12:13]
	v_cndmask_b32_e64 v0, 0, 1, s[16:17]
	v_cmp_ne_u32_e32 vcc, 0, v0
	s_cbranch_vccz .LBB0_898
	s_and_saveexec_b64 s[16:17], s[12:13]
	s_xor_b64 s[12:13], exec, s[16:17]
	v_cmp_lg_f32_e64 s[52:53], s5, v1
	s_nop 1
	v_cndmask_b32_e64 v48, 0, v1, s[52:53]
	s_or_saveexec_b64 s[12:13], s[12:13]
	v_mov_b32_e32 v0, 1.0
	s_xor_b64 exec, exec, s[12:13]
	v_max_f32_e32 v0, v1, v1
	v_max_f32_e32 v48, 0, v0
	v_exp_f32_e64 v0, -v48
	s_or_b64 s[52:53], s[52:53], exec
	s_or_b64 exec, exec, s[12:13]
	v_add_f32_e32 v219, v219, v48
	v_pk_add_f32 v[80:81], v[80:81], v[48:49] op_sel_hi:[1,0] neg_lo:[0,1] neg_hi:[0,1]
	v_pk_add_f32 v[96:97], v[96:97], v[48:49] op_sel_hi:[1,0] neg_lo:[0,1] neg_hi:[0,1]
	v_pk_add_f32 v[82:83], v[82:83], v[48:49] op_sel_hi:[1,0] neg_lo:[0,1] neg_hi:[0,1]
	v_pk_add_f32 v[98:99], v[98:99], v[48:49] op_sel_hi:[1,0] neg_lo:[0,1] neg_hi:[0,1]
	v_pk_add_f32 v[84:85], v[84:85], v[48:49] op_sel_hi:[1,0] neg_lo:[0,1] neg_hi:[0,1]
	v_pk_add_f32 v[100:101], v[100:101], v[48:49] op_sel_hi:[1,0] neg_lo:[0,1] neg_hi:[0,1]
	v_pk_add_f32 v[86:87], v[86:87], v[48:49] op_sel_hi:[1,0] neg_lo:[0,1] neg_hi:[0,1]
	v_pk_add_f32 v[102:103], v[102:103], v[48:49] op_sel_hi:[1,0] neg_lo:[0,1] neg_hi:[0,1]
	v_pk_add_f32 v[88:89], v[88:89], v[48:49] op_sel_hi:[1,0] neg_lo:[0,1] neg_hi:[0,1]
	v_pk_add_f32 v[104:105], v[104:105], v[48:49] op_sel_hi:[1,0] neg_lo:[0,1] neg_hi:[0,1]
	v_pk_add_f32 v[90:91], v[90:91], v[48:49] op_sel_hi:[1,0] neg_lo:[0,1] neg_hi:[0,1]
	v_pk_add_f32 v[106:107], v[106:107], v[48:49] op_sel_hi:[1,0] neg_lo:[0,1] neg_hi:[0,1]
	v_pk_add_f32 v[92:93], v[92:93], v[48:49] op_sel_hi:[1,0] neg_lo:[0,1] neg_hi:[0,1]
	v_pk_add_f32 v[108:109], v[108:109], v[48:49] op_sel_hi:[1,0] neg_lo:[0,1] neg_hi:[0,1]
	v_pk_add_f32 v[94:95], v[94:95], v[48:49] op_sel_hi:[1,0] neg_lo:[0,1] neg_hi:[0,1]
	v_pk_add_f32 v[110:111], v[110:111], v[48:49] op_sel_hi:[1,0] neg_lo:[0,1] neg_hi:[0,1]
	v_xor_b32_e32 v48, 0x80000000, v219
	v_mul_f32_e32 v209, v209, v0
	v_pk_mul_f32 v[46:47], v[46:47], v[0:1] op_sel_hi:[1,0]
	v_pk_mul_f32 v[44:45], v[44:45], v[0:1] op_sel_hi:[1,0]
	v_pk_mul_f32 v[42:43], v[42:43], v[0:1] op_sel_hi:[1,0]
	v_pk_mul_f32 v[40:41], v[40:41], v[0:1] op_sel_hi:[1,0]
	v_pk_mul_f32 v[38:39], v[38:39], v[0:1] op_sel_hi:[1,0]
	v_pk_mul_f32 v[36:37], v[36:37], v[0:1] op_sel_hi:[1,0]
	v_pk_mul_f32 v[34:35], v[34:35], v[0:1] op_sel_hi:[1,0]
	v_pk_mul_f32 v[32:33], v[32:33], v[0:1] op_sel_hi:[1,0]
	v_pk_mul_f32 v[30:31], v[30:31], v[0:1] op_sel_hi:[1,0]
	v_pk_mul_f32 v[28:29], v[28:29], v[0:1] op_sel_hi:[1,0]
	v_pk_mul_f32 v[26:27], v[26:27], v[0:1] op_sel_hi:[1,0]
	v_pk_mul_f32 v[24:25], v[24:25], v[0:1] op_sel_hi:[1,0]
	v_pk_mul_f32 v[22:23], v[22:23], v[0:1] op_sel_hi:[1,0]
	v_pk_mul_f32 v[20:21], v[20:21], v[0:1] op_sel_hi:[1,0]
	v_pk_mul_f32 v[18:19], v[18:19], v[0:1] op_sel_hi:[1,0]
	v_pk_mul_f32 v[16:17], v[16:17], v[0:1] op_sel_hi:[1,0]
	v_mov_b32_e32 v49, v48
	v_mov_b32_e32 v50, v48
	v_mov_b32_e32 v51, v48
	v_mov_b32_e32 v52, v48
	v_mov_b32_e32 v53, v48
	v_mov_b32_e32 v54, v48
	v_mov_b32_e32 v55, v48
	v_mov_b32_e32 v56, v48
	v_mov_b32_e32 v57, v48
	v_mov_b32_e32 v58, v48
	v_mov_b32_e32 v59, v48
	v_mov_b32_e32 v60, v48
	v_mov_b32_e32 v61, v48
	v_mov_b32_e32 v62, v48
	v_mov_b32_e32 v63, v48
	v_mov_b32_e32 v79, v48
	v_mov_b32_e32 v78, v48
	v_mov_b32_e32 v77, v48
	v_mov_b32_e32 v76, v48
	v_mov_b32_e32 v75, v48
	v_mov_b32_e32 v74, v48
	v_mov_b32_e32 v73, v48
	v_mov_b32_e32 v72, v48
	v_mov_b32_e32 v71, v48
	v_mov_b32_e32 v70, v48
	v_mov_b32_e32 v69, v48
	v_mov_b32_e32 v68, v48
	v_mov_b32_e32 v67, v48
	v_mov_b32_e32 v66, v48
	v_mov_b32_e32 v65, v48
	v_mov_b32_e32 v64, v48

.LBB0_962:
	s_or_b64 exec, exec, s[16:17]
	s_nop 0
	s_xor_b64 s[12:13], s[20:21], -1
	v_max3_f32 v0, v96, v97, v80
	v_max3_f32 v1, v98, v99, v81
	v_max3_f32 v0, v0, v82, v83
	v_max3_f32 v1, v1, v102, v103
	v_max3_f32 v0, v0, v100, v101
	v_max3_f32 v1, v1, v86, v87
	v_max3_f32 v0, v0, v84, v85
	v_max3_f32 v1, v1, v106, v107
	v_max3_f32 v0, v0, v104, v105
	v_max3_f32 v1, v1, v90, v91
	v_max3_f32 v0, v0, v88, v89
	v_max3_f32 v1, v1, v110, v111
	v_max3_f32 v0, v0, v108, v109
	v_max3_f32 v1, v1, v94, v95
	v_max3_f32 v0, v0, v92, v93
	v_max_f32_e32 v1, v1, v1
	v_max_f32_e32 v0, v0, v0
	v_max_f32_e32 v0, v0, v1
	v_mov_b32_e32 v1, v0
	s_nop 1
	v_permlane32_swap_b32_e32 v0, v1
	v_max_f32_e32 v1, v1, v1
	v_max_f32_e32 v0, v0, v0
	v_max_f32_e32 v1, v0, v1
	v_cmp_lt_f32_e32 vcc, s14, v1
	s_or_b64 s[16:17], vcc, s[12:13]
	v_cndmask_b32_e64 v0, 0, 1, s[16:17]
	v_cmp_ne_u32_e32 vcc, 0, v0
	s_cbranch_vccz .LBB0_968
	s_and_saveexec_b64 s[16:17], s[12:13]
	s_xor_b64 s[12:13], exec, s[16:17]
	v_cmp_lg_f32_e64 s[20:21], s5, v1
	s_nop 1
	v_cndmask_b32_e64 v48, 0, v1, s[20:21]
	s_or_saveexec_b64 s[12:13], s[12:13]
	v_mov_b32_e32 v0, 1.0
	s_xor_b64 exec, exec, s[12:13]
	v_max_f32_e32 v0, v1, v1
	v_max_f32_e32 v48, 0, v0
	v_exp_f32_e64 v0, -v48
	s_or_b64 s[20:21], s[20:21], exec
	s_or_b64 exec, exec, s[12:13]
	v_add_f32_e32 v227, v227, v48
	v_xor_b32_e32 v64, 0x80000000, v227
	v_pk_add_f32 v[96:97], v[96:97], v[48:49] op_sel_hi:[1,0] neg_lo:[0,1] neg_hi:[0,1]
	v_pk_add_f32 v[80:81], v[80:81], v[48:49] op_sel_hi:[1,0] neg_lo:[0,1] neg_hi:[0,1]
	v_pk_add_f32 v[98:99], v[98:99], v[48:49] op_sel_hi:[1,0] neg_lo:[0,1] neg_hi:[0,1]
	v_pk_add_f32 v[82:83], v[82:83], v[48:49] op_sel_hi:[1,0] neg_lo:[0,1] neg_hi:[0,1]
	v_pk_add_f32 v[100:101], v[100:101], v[48:49] op_sel_hi:[1,0] neg_lo:[0,1] neg_hi:[0,1]
	v_pk_add_f32 v[84:85], v[84:85], v[48:49] op_sel_hi:[1,0] neg_lo:[0,1] neg_hi:[0,1]
	v_pk_add_f32 v[102:103], v[102:103], v[48:49] op_sel_hi:[1,0] neg_lo:[0,1] neg_hi:[0,1]
	v_pk_add_f32 v[86:87], v[86:87], v[48:49] op_sel_hi:[1,0] neg_lo:[0,1] neg_hi:[0,1]
	v_pk_add_f32 v[104:105], v[104:105], v[48:49] op_sel_hi:[1,0] neg_lo:[0,1] neg_hi:[0,1]
	v_pk_add_f32 v[88:89], v[88:89], v[48:49] op_sel_hi:[1,0] neg_lo:[0,1] neg_hi:[0,1]
	v_pk_add_f32 v[106:107], v[106:107], v[48:49] op_sel_hi:[1,0] neg_lo:[0,1] neg_hi:[0,1]
	v_pk_add_f32 v[90:91], v[90:91], v[48:49] op_sel_hi:[1,0] neg_lo:[0,1] neg_hi:[0,1]
	v_pk_add_f32 v[108:109], v[108:109], v[48:49] op_sel_hi:[1,0] neg_lo:[0,1] neg_hi:[0,1]
	v_pk_add_f32 v[92:93], v[92:93], v[48:49] op_sel_hi:[1,0] neg_lo:[0,1] neg_hi:[0,1]
	v_pk_add_f32 v[110:111], v[110:111], v[48:49] op_sel_hi:[1,0] neg_lo:[0,1] neg_hi:[0,1]
	v_pk_add_f32 v[94:95], v[94:95], v[48:49] op_sel_hi:[1,0] neg_lo:[0,1] neg_hi:[0,1]
	v_mul_f32_e32 v226, v226, v0
	v_pk_mul_f32 v[46:47], v[46:47], v[0:1] op_sel_hi:[1,0]
	v_pk_mul_f32 v[44:45], v[44:45], v[0:1] op_sel_hi:[1,0]
	v_pk_mul_f32 v[42:43], v[42:43], v[0:1] op_sel_hi:[1,0]
	v_pk_mul_f32 v[40:41], v[40:41], v[0:1] op_sel_hi:[1,0]
	v_pk_mul_f32 v[38:39], v[38:39], v[0:1] op_sel_hi:[1,0]
	v_pk_mul_f32 v[36:37], v[36:37], v[0:1] op_sel_hi:[1,0]
	v_pk_mul_f32 v[34:35], v[34:35], v[0:1] op_sel_hi:[1,0]
	v_pk_mul_f32 v[32:33], v[32:33], v[0:1] op_sel_hi:[1,0]
	v_pk_mul_f32 v[30:31], v[30:31], v[0:1] op_sel_hi:[1,0]
	v_pk_mul_f32 v[28:29], v[28:29], v[0:1] op_sel_hi:[1,0]
	v_pk_mul_f32 v[26:27], v[26:27], v[0:1] op_sel_hi:[1,0]
	v_pk_mul_f32 v[24:25], v[24:25], v[0:1] op_sel_hi:[1,0]
	v_pk_mul_f32 v[22:23], v[22:23], v[0:1] op_sel_hi:[1,0]
	v_pk_mul_f32 v[20:21], v[20:21], v[0:1] op_sel_hi:[1,0]
	v_pk_mul_f32 v[18:19], v[18:19], v[0:1] op_sel_hi:[1,0]
	v_pk_mul_f32 v[16:17], v[16:17], v[0:1] op_sel_hi:[1,0]
	v_mov_b32_e32 v65, v64
	v_mov_b32_e32 v66, v64
	v_mov_b32_e32 v67, v64
	v_mov_b32_e32 v68, v64
	v_mov_b32_e32 v69, v64
	v_mov_b32_e32 v70, v64
	v_mov_b32_e32 v71, v64
	v_mov_b32_e32 v72, v64
	v_mov_b32_e32 v73, v64
	v_mov_b32_e32 v74, v64
	v_mov_b32_e32 v75, v64
	v_mov_b32_e32 v76, v64
	v_mov_b32_e32 v77, v64
	v_mov_b32_e32 v78, v64
	v_mov_b32_e32 v79, v64
	v_mov_b32_e32 v63, v64
	v_mov_b32_e32 v62, v64
	v_mov_b32_e32 v61, v64
	v_mov_b32_e32 v60, v64
	v_mov_b32_e32 v59, v64
	v_mov_b32_e32 v58, v64
	v_mov_b32_e32 v57, v64
	v_mov_b32_e32 v56, v64
	v_mov_b32_e32 v55, v64
	v_mov_b32_e32 v54, v64
	v_mov_b32_e32 v53, v64
	v_mov_b32_e32 v52, v64
	v_mov_b32_e32 v51, v64
	v_mov_b32_e32 v50, v64
	v_mov_b32_e32 v49, v64
	v_mov_b32_e32 v48, v64
	s_branch .LBB0_969

.LBB0_982:
	s_or_b64 exec, exec, s[16:17]
	s_nop 0
	s_xor_b64 s[16:17], s[20:21], -1
	v_max3_f32 v0, v80, v81, v64
	v_max3_f32 v1, v82, v83, v65
	v_max3_f32 v0, v0, v66, v67
	v_max3_f32 v1, v1, v86, v87
	v_max3_f32 v0, v0, v84, v85
	v_max3_f32 v1, v1, v70, v71
	v_max3_f32 v0, v0, v68, v69
	v_max3_f32 v1, v1, v90, v91
	v_max3_f32 v0, v0, v88, v89
	v_max3_f32 v1, v1, v74, v75
	v_max3_f32 v0, v0, v72, v73
	v_max3_f32 v1, v1, v94, v95
	v_max3_f32 v0, v0, v92, v93
	v_max3_f32 v1, v1, v78, v79
	v_max3_f32 v0, v0, v76, v77
	v_max_f32_e32 v1, v1, v1
	v_max_f32_e32 v0, v0, v0
	v_max_f32_e32 v0, v0, v1
	v_mov_b32_e32 v1, v0
	s_nop 1
	v_permlane32_swap_b32_e32 v0, v1
	v_max_f32_e32 v1, v1, v1
	v_max_f32_e32 v0, v0, v0
	v_max_f32_e32 v1, v0, v1
	v_cmp_lt_f32_e32 vcc, s14, v1
	s_or_b64 s[24:25], vcc, s[16:17]
	v_cndmask_b32_e64 v0, 0, 1, s[24:25]
	v_cmp_ne_u32_e32 vcc, 0, v0
	s_cbranch_vccz .LBB0_988
	s_and_saveexec_b64 s[24:25], s[16:17]
	s_xor_b64 s[16:17], exec, s[24:25]
	v_cmp_lg_f32_e64 s[20:21], s5, v1
	s_nop 1
	v_cndmask_b32_e64 v48, 0, v1, s[20:21]
	s_or_saveexec_b64 s[16:17], s[16:17]
	v_mov_b32_e32 v0, 1.0
	s_xor_b64 exec, exec, s[16:17]
	v_max_f32_e32 v0, v1, v1
	v_max_f32_e32 v48, 0, v0
	v_exp_f32_e64 v0, -v48
	s_or_b64 s[20:21], s[20:21], exec
	s_or_b64 exec, exec, s[16:17]
	v_add_f32_e32 v227, v227, v48
	v_xor_b32_e32 v63, 0x80000000, v227
	v_pk_add_f32 v[80:81], v[80:81], v[48:49] op_sel_hi:[1,0] neg_lo:[0,1] neg_hi:[0,1]
	v_pk_add_f32 v[64:65], v[64:65], v[48:49] op_sel_hi:[1,0] neg_lo:[0,1] neg_hi:[0,1]
	v_pk_add_f32 v[82:83], v[82:83], v[48:49] op_sel_hi:[1,0] neg_lo:[0,1] neg_hi:[0,1]
	v_pk_add_f32 v[66:67], v[66:67], v[48:49] op_sel_hi:[1,0] neg_lo:[0,1] neg_hi:[0,1]
	v_pk_add_f32 v[84:85], v[84:85], v[48:49] op_sel_hi:[1,0] neg_lo:[0,1] neg_hi:[0,1]
	v_pk_add_f32 v[68:69], v[68:69], v[48:49] op_sel_hi:[1,0] neg_lo:[0,1] neg_hi:[0,1]
	v_pk_add_f32 v[86:87], v[86:87], v[48:49] op_sel_hi:[1,0] neg_lo:[0,1] neg_hi:[0,1]
	v_pk_add_f32 v[70:71], v[70:71], v[48:49] op_sel_hi:[1,0] neg_lo:[0,1] neg_hi:[0,1]
	v_pk_add_f32 v[88:89], v[88:89], v[48:49] op_sel_hi:[1,0] neg_lo:[0,1] neg_hi:[0,1]
	v_pk_add_f32 v[72:73], v[72:73], v[48:49] op_sel_hi:[1,0] neg_lo:[0,1] neg_hi:[0,1]
	v_pk_add_f32 v[90:91], v[90:91], v[48:49] op_sel_hi:[1,0] neg_lo:[0,1] neg_hi:[0,1]
	v_pk_add_f32 v[74:75], v[74:75], v[48:49] op_sel_hi:[1,0] neg_lo:[0,1] neg_hi:[0,1]
	v_pk_add_f32 v[92:93], v[92:93], v[48:49] op_sel_hi:[1,0] neg_lo:[0,1] neg_hi:[0,1]
	v_pk_add_f32 v[76:77], v[76:77], v[48:49] op_sel_hi:[1,0] neg_lo:[0,1] neg_hi:[0,1]
	v_pk_add_f32 v[94:95], v[94:95], v[48:49] op_sel_hi:[1,0] neg_lo:[0,1] neg_hi:[0,1]
	v_pk_add_f32 v[78:79], v[78:79], v[48:49] op_sel_hi:[1,0] neg_lo:[0,1] neg_hi:[0,1]
	v_mul_f32_e32 v226, v226, v0
	v_pk_mul_f32 v[46:47], v[46:47], v[0:1] op_sel_hi:[1,0]
	v_pk_mul_f32 v[44:45], v[44:45], v[0:1] op_sel_hi:[1,0]
	v_pk_mul_f32 v[42:43], v[42:43], v[0:1] op_sel_hi:[1,0]
	v_pk_mul_f32 v[40:41], v[40:41], v[0:1] op_sel_hi:[1,0]
	v_pk_mul_f32 v[38:39], v[38:39], v[0:1] op_sel_hi:[1,0]
	v_pk_mul_f32 v[36:37], v[36:37], v[0:1] op_sel_hi:[1,0]
	v_pk_mul_f32 v[34:35], v[34:35], v[0:1] op_sel_hi:[1,0]
	v_pk_mul_f32 v[32:33], v[32:33], v[0:1] op_sel_hi:[1,0]
	v_pk_mul_f32 v[30:31], v[30:31], v[0:1] op_sel_hi:[1,0]
	v_pk_mul_f32 v[28:29], v[28:29], v[0:1] op_sel_hi:[1,0]
	v_pk_mul_f32 v[26:27], v[26:27], v[0:1] op_sel_hi:[1,0]
	v_pk_mul_f32 v[24:25], v[24:25], v[0:1] op_sel_hi:[1,0]
	v_pk_mul_f32 v[22:23], v[22:23], v[0:1] op_sel_hi:[1,0]
	v_pk_mul_f32 v[20:21], v[20:21], v[0:1] op_sel_hi:[1,0]
	v_pk_mul_f32 v[18:19], v[18:19], v[0:1] op_sel_hi:[1,0]
	v_pk_mul_f32 v[16:17], v[16:17], v[0:1] op_sel_hi:[1,0]
	v_mov_b32_e32 v62, v63
	v_mov_b32_e32 v61, v63
	v_mov_b32_e32 v60, v63
	v_mov_b32_e32 v59, v63
	v_mov_b32_e32 v58, v63
	v_mov_b32_e32 v57, v63
	v_mov_b32_e32 v56, v63
	v_mov_b32_e32 v55, v63
	v_mov_b32_e32 v54, v63
	v_mov_b32_e32 v53, v63
	v_mov_b32_e32 v52, v63
	v_mov_b32_e32 v51, v63
	v_mov_b32_e32 v50, v63
	v_mov_b32_e32 v49, v63
	v_mov_b32_e32 v48, v63

.LBB0_1003:
	s_nop 3
	s_xor_b64 s[16:17], s[94:95], -1
	v_max3_f32 v0, v80, v81, v96
	v_max3_f32 v1, v82, v83, v97
	v_max3_f32 v0, v0, v98, v99
	v_max3_f32 v1, v1, v86, v87
	v_max3_f32 v0, v0, v84, v85
	v_max3_f32 v1, v1, v102, v103
	v_max3_f32 v0, v0, v100, v101
	v_max3_f32 v1, v1, v90, v91
	v_max3_f32 v0, v0, v88, v89
	v_max3_f32 v1, v1, v106, v107
	v_max3_f32 v0, v0, v104, v105
	v_max3_f32 v1, v1, v94, v95
	v_max3_f32 v0, v0, v92, v93
	v_max3_f32 v1, v1, v110, v111
	v_max3_f32 v0, v0, v108, v109
	v_max_f32_e32 v1, v1, v1
	v_max_f32_e32 v0, v0, v0
	v_max_f32_e32 v0, v0, v1
	v_mov_b32_e32 v1, v0
	s_nop 1
	v_permlane32_swap_b32_e32 v0, v1
	v_max_f32_e32 v1, v1, v1
	v_max_f32_e32 v0, v0, v0
	v_max_f32_e32 v1, v0, v1
	v_cmp_lt_f32_e32 vcc, s14, v1
	s_or_b64 s[18:19], vcc, s[16:17]
	v_cndmask_b32_e64 v0, 0, 1, s[18:19]
	v_cmp_ne_u32_e32 vcc, 0, v0
	s_cbranch_vccz .LBB0_1009
	s_and_saveexec_b64 s[18:19], s[16:17]
	s_xor_b64 s[16:17], exec, s[18:19]
	v_cmp_lg_f32_e64 s[94:95], s5, v1
	s_nop 1
	v_cndmask_b32_e64 v48, 0, v1, s[94:95]
	s_or_saveexec_b64 s[16:17], s[16:17]
	v_mov_b32_e32 v0, 1.0
	s_xor_b64 exec, exec, s[16:17]
	v_max_f32_e32 v0, v1, v1
	v_max_f32_e32 v48, 0, v0
	v_exp_f32_e64 v0, -v48
	s_or_b64 s[94:95], s[94:95], exec
	s_or_b64 exec, exec, s[16:17]
	v_add_f32_e32 v248, v248, v48
	v_xor_b32_e32 v64, 0x80000000, v248
	v_pk_add_f32 v[80:81], v[80:81], v[48:49] op_sel_hi:[1,0] neg_lo:[0,1] neg_hi:[0,1]
	v_pk_add_f32 v[96:97], v[96:97], v[48:49] op_sel_hi:[1,0] neg_lo:[0,1] neg_hi:[0,1]
	v_pk_add_f32 v[82:83], v[82:83], v[48:49] op_sel_hi:[1,0] neg_lo:[0,1] neg_hi:[0,1]
	v_pk_add_f32 v[98:99], v[98:99], v[48:49] op_sel_hi:[1,0] neg_lo:[0,1] neg_hi:[0,1]
	v_pk_add_f32 v[84:85], v[84:85], v[48:49] op_sel_hi:[1,0] neg_lo:[0,1] neg_hi:[0,1]
	v_pk_add_f32 v[100:101], v[100:101], v[48:49] op_sel_hi:[1,0] neg_lo:[0,1] neg_hi:[0,1]
	v_pk_add_f32 v[86:87], v[86:87], v[48:49] op_sel_hi:[1,0] neg_lo:[0,1] neg_hi:[0,1]
	v_pk_add_f32 v[102:103], v[102:103], v[48:49] op_sel_hi:[1,0] neg_lo:[0,1] neg_hi:[0,1]
	v_pk_add_f32 v[88:89], v[88:89], v[48:49] op_sel_hi:[1,0] neg_lo:[0,1] neg_hi:[0,1]
	v_pk_add_f32 v[104:105], v[104:105], v[48:49] op_sel_hi:[1,0] neg_lo:[0,1] neg_hi:[0,1]
	v_pk_add_f32 v[90:91], v[90:91], v[48:49] op_sel_hi:[1,0] neg_lo:[0,1] neg_hi:[0,1]
	v_pk_add_f32 v[106:107], v[106:107], v[48:49] op_sel_hi:[1,0] neg_lo:[0,1] neg_hi:[0,1]
	v_pk_add_f32 v[92:93], v[92:93], v[48:49] op_sel_hi:[1,0] neg_lo:[0,1] neg_hi:[0,1]
	v_pk_add_f32 v[108:109], v[108:109], v[48:49] op_sel_hi:[1,0] neg_lo:[0,1] neg_hi:[0,1]
	v_pk_add_f32 v[94:95], v[94:95], v[48:49] op_sel_hi:[1,0] neg_lo:[0,1] neg_hi:[0,1]
	v_pk_add_f32 v[110:111], v[110:111], v[48:49] op_sel_hi:[1,0] neg_lo:[0,1] neg_hi:[0,1]
	v_mul_f32_e32 v222, v222, v0
	v_pk_mul_f32 v[46:47], v[46:47], v[0:1] op_sel_hi:[1,0]
	v_pk_mul_f32 v[44:45], v[44:45], v[0:1] op_sel_hi:[1,0]
	v_pk_mul_f32 v[42:43], v[42:43], v[0:1] op_sel_hi:[1,0]
	v_pk_mul_f32 v[40:41], v[40:41], v[0:1] op_sel_hi:[1,0]
	v_pk_mul_f32 v[38:39], v[38:39], v[0:1] op_sel_hi:[1,0]
	v_pk_mul_f32 v[36:37], v[36:37], v[0:1] op_sel_hi:[1,0]
	v_pk_mul_f32 v[34:35], v[34:35], v[0:1] op_sel_hi:[1,0]
	v_pk_mul_f32 v[32:33], v[32:33], v[0:1] op_sel_hi:[1,0]
	v_pk_mul_f32 v[30:31], v[30:31], v[0:1] op_sel_hi:[1,0]
	v_pk_mul_f32 v[28:29], v[28:29], v[0:1] op_sel_hi:[1,0]
	v_pk_mul_f32 v[26:27], v[26:27], v[0:1] op_sel_hi:[1,0]
	v_pk_mul_f32 v[24:25], v[24:25], v[0:1] op_sel_hi:[1,0]
	v_pk_mul_f32 v[22:23], v[22:23], v[0:1] op_sel_hi:[1,0]
	v_pk_mul_f32 v[20:21], v[20:21], v[0:1] op_sel_hi:[1,0]
	v_pk_mul_f32 v[18:19], v[18:19], v[0:1] op_sel_hi:[1,0]
	v_pk_mul_f32 v[16:17], v[16:17], v[0:1] op_sel_hi:[1,0]
	v_mov_b32_e32 v65, v64
	v_mov_b32_e32 v66, v64
	v_mov_b32_e32 v67, v64
	v_mov_b32_e32 v68, v64
	v_mov_b32_e32 v69, v64
	v_mov_b32_e32 v70, v64
	v_mov_b32_e32 v71, v64
	v_mov_b32_e32 v72, v64
	v_mov_b32_e32 v73, v64
	v_mov_b32_e32 v74, v64
	v_mov_b32_e32 v75, v64
	v_mov_b32_e32 v76, v64
	v_mov_b32_e32 v77, v64
	v_mov_b32_e32 v78, v64
	v_mov_b32_e32 v79, v64
	v_mov_b32_e32 v63, v64
	v_mov_b32_e32 v62, v64
	v_mov_b32_e32 v61, v64
	v_mov_b32_e32 v60, v64
	v_mov_b32_e32 v59, v64
	v_mov_b32_e32 v58, v64
	v_mov_b32_e32 v57, v64
	v_mov_b32_e32 v56, v64
	v_mov_b32_e32 v55, v64
	v_mov_b32_e32 v54, v64
	v_mov_b32_e32 v53, v64
	v_mov_b32_e32 v52, v64
	v_mov_b32_e32 v51, v64
	v_mov_b32_e32 v50, v64
	v_mov_b32_e32 v49, v64
	v_mov_b32_e32 v48, v64
	s_branch .LBB0_1010

.LBB0_1017:
	s_nop 3
	s_xor_b64 s[12:13], s[94:95], -1
	v_max3_f32 v0, v80, v81, v64
	v_max3_f32 v1, v82, v83, v65
	v_max3_f32 v0, v0, v66, v67
	v_max3_f32 v1, v1, v86, v87
	v_max3_f32 v0, v0, v84, v85
	v_max3_f32 v1, v1, v70, v71
	v_max3_f32 v0, v0, v68, v69
	v_max3_f32 v1, v1, v90, v91
	v_max3_f32 v0, v0, v88, v89
	v_max3_f32 v1, v1, v74, v75
	v_max3_f32 v0, v0, v72, v73
	v_max3_f32 v1, v1, v94, v95
	v_max3_f32 v0, v0, v92, v93
	v_max3_f32 v1, v1, v78, v79
	v_max3_f32 v0, v0, v76, v77
	v_max_f32_e32 v1, v1, v1
	v_max_f32_e32 v0, v0, v0
	v_max_f32_e32 v0, v0, v1
	v_mov_b32_e32 v1, v0
	s_nop 1
	v_permlane32_swap_b32_e32 v0, v1
	v_max_f32_e32 v1, v1, v1
	v_max_f32_e32 v0, v0, v0
	v_max_f32_e32 v1, v0, v1
	v_cmp_lt_f32_e32 vcc, s14, v1
	s_or_b64 s[16:17], vcc, s[12:13]
	v_cndmask_b32_e64 v0, 0, 1, s[16:17]
	v_cmp_ne_u32_e32 vcc, 0, v0
	s_cbranch_vccz .LBB0_1023
	s_and_saveexec_b64 s[16:17], s[12:13]
	s_xor_b64 s[12:13], exec, s[16:17]
	v_cmp_lg_f32_e64 s[94:95], s5, v1
	s_nop 1
	v_cndmask_b32_e64 v48, 0, v1, s[94:95]
	s_or_saveexec_b64 s[12:13], s[12:13]
	v_mov_b32_e32 v0, 1.0
	s_xor_b64 exec, exec, s[12:13]
	v_max_f32_e32 v0, v1, v1
	v_max_f32_e32 v48, 0, v0
	v_exp_f32_e64 v0, -v48
	s_or_b64 s[94:95], s[94:95], exec
	s_or_b64 exec, exec, s[12:13]
	v_add_f32_e32 v248, v248, v48
	v_xor_b32_e32 v63, 0x80000000, v248
	v_pk_add_f32 v[80:81], v[80:81], v[48:49] op_sel_hi:[1,0] neg_lo:[0,1] neg_hi:[0,1]
	v_pk_add_f32 v[64:65], v[64:65], v[48:49] op_sel_hi:[1,0] neg_lo:[0,1] neg_hi:[0,1]
	v_pk_add_f32 v[82:83], v[82:83], v[48:49] op_sel_hi:[1,0] neg_lo:[0,1] neg_hi:[0,1]
	v_pk_add_f32 v[66:67], v[66:67], v[48:49] op_sel_hi:[1,0] neg_lo:[0,1] neg_hi:[0,1]
	v_pk_add_f32 v[84:85], v[84:85], v[48:49] op_sel_hi:[1,0] neg_lo:[0,1] neg_hi:[0,1]
	v_pk_add_f32 v[68:69], v[68:69], v[48:49] op_sel_hi:[1,0] neg_lo:[0,1] neg_hi:[0,1]
	v_pk_add_f32 v[86:87], v[86:87], v[48:49] op_sel_hi:[1,0] neg_lo:[0,1] neg_hi:[0,1]
	v_pk_add_f32 v[70:71], v[70:71], v[48:49] op_sel_hi:[1,0] neg_lo:[0,1] neg_hi:[0,1]
	v_pk_add_f32 v[88:89], v[88:89], v[48:49] op_sel_hi:[1,0] neg_lo:[0,1] neg_hi:[0,1]
	v_pk_add_f32 v[72:73], v[72:73], v[48:49] op_sel_hi:[1,0] neg_lo:[0,1] neg_hi:[0,1]
	v_pk_add_f32 v[90:91], v[90:91], v[48:49] op_sel_hi:[1,0] neg_lo:[0,1] neg_hi:[0,1]
	v_pk_add_f32 v[74:75], v[74:75], v[48:49] op_sel_hi:[1,0] neg_lo:[0,1] neg_hi:[0,1]
	v_pk_add_f32 v[92:93], v[92:93], v[48:49] op_sel_hi:[1,0] neg_lo:[0,1] neg_hi:[0,1]
	v_pk_add_f32 v[76:77], v[76:77], v[48:49] op_sel_hi:[1,0] neg_lo:[0,1] neg_hi:[0,1]
	v_pk_add_f32 v[94:95], v[94:95], v[48:49] op_sel_hi:[1,0] neg_lo:[0,1] neg_hi:[0,1]
	v_pk_add_f32 v[78:79], v[78:79], v[48:49] op_sel_hi:[1,0] neg_lo:[0,1] neg_hi:[0,1]
	v_mul_f32_e32 v222, v222, v0
	v_pk_mul_f32 v[46:47], v[46:47], v[0:1] op_sel_hi:[1,0]
	v_pk_mul_f32 v[44:45], v[44:45], v[0:1] op_sel_hi:[1,0]
	v_pk_mul_f32 v[42:43], v[42:43], v[0:1] op_sel_hi:[1,0]
	v_pk_mul_f32 v[40:41], v[40:41], v[0:1] op_sel_hi:[1,0]
	v_pk_mul_f32 v[38:39], v[38:39], v[0:1] op_sel_hi:[1,0]
	v_pk_mul_f32 v[36:37], v[36:37], v[0:1] op_sel_hi:[1,0]
	v_pk_mul_f32 v[34:35], v[34:35], v[0:1] op_sel_hi:[1,0]
	v_pk_mul_f32 v[32:33], v[32:33], v[0:1] op_sel_hi:[1,0]
	v_pk_mul_f32 v[30:31], v[30:31], v[0:1] op_sel_hi:[1,0]
	v_pk_mul_f32 v[28:29], v[28:29], v[0:1] op_sel_hi:[1,0]
	v_pk_mul_f32 v[26:27], v[26:27], v[0:1] op_sel_hi:[1,0]
	v_pk_mul_f32 v[24:25], v[24:25], v[0:1] op_sel_hi:[1,0]
	v_pk_mul_f32 v[22:23], v[22:23], v[0:1] op_sel_hi:[1,0]
	v_pk_mul_f32 v[20:21], v[20:21], v[0:1] op_sel_hi:[1,0]
	v_pk_mul_f32 v[18:19], v[18:19], v[0:1] op_sel_hi:[1,0]
	v_pk_mul_f32 v[16:17], v[16:17], v[0:1] op_sel_hi:[1,0]
	v_mov_b32_e32 v62, v63
	v_mov_b32_e32 v61, v63
	v_mov_b32_e32 v60, v63
	v_mov_b32_e32 v59, v63
	v_mov_b32_e32 v58, v63
	v_mov_b32_e32 v57, v63
	v_mov_b32_e32 v56, v63
	v_mov_b32_e32 v55, v63
	v_mov_b32_e32 v54, v63
	v_mov_b32_e32 v53, v63
	v_mov_b32_e32 v52, v63
	v_mov_b32_e32 v51, v63
	v_mov_b32_e32 v50, v63
	v_mov_b32_e32 v49, v63
	v_mov_b32_e32 v48, v63
